# L2 residency in the mixer, isolating further: only the short-conv loop's 12 loads non-temporal (its 4 stores left default)
# speedup vs baseline: 1.0146x; 1.0061x over previous
.LBB0_113:
	s_nop 0
	v_lshl_add_u64 v[34:35], s[34:35], 0, v[0:1]
	v_add_co_u32_e32 v36, vcc, 0x7100000, v34
	s_mov_b32 s4, 0x7100000
	s_nop 0
	v_addc_co_u32_e32 v37, vcc, 0, v35, vcc
	v_add_co_u32_e32 v34, vcc, 0x7101000, v34
	global_load_dwordx4 v[70:73], v[36:37], off offset:3072 nt
	s_nop 0
	v_addc_co_u32_e32 v35, vcc, 0, v35, vcc
	global_load_dwordx4 v[78:81], v[34:35], off nt
	global_load_dwordx4 v[74:77], v[34:35], off offset:1024 nt
	v_lshl_add_u64 v[34:35], s[28:29], 0, v[0:1]
	v_add_co_u32_e32 v36, vcc, s4, v34
	s_mov_b32 s4, 0x7101000
	s_nop 0
	v_addc_co_u32_e32 v37, vcc, 0, v35, vcc
	v_add_co_u32_e32 v34, vcc, s4, v34
	global_load_dwordx4 v[58:61], v[36:37], off offset:3072 nt
	s_nop 0
	v_addc_co_u32_e32 v35, vcc, 0, v35, vcc
	global_load_dwordx4 v[66:69], v[34:35], off nt
	global_load_dwordx4 v[62:65], v[34:35], off offset:1024 nt
	s_add_i32 s42, s24, 2
	v_mad_i64_i32 v[34:35], s[4:5], s42, v245, v[82:83]
	global_load_dwordx4 v[38:41], v[34:35], off offset:3072 nt
	v_add_co_u32_e32 v34, vcc, s45, v34
	s_add_i32 s36, s24, 3
	s_nop 0
	v_addc_co_u32_e32 v35, vcc, 0, v35, vcc
	global_load_dwordx4 v[54:57], v[34:35], off nt
	global_load_dwordx4 v[50:53], v[34:35], off offset:1024 nt
	v_mad_i64_i32 v[42:43], s[4:5], s36, v245, v[82:83]
	global_load_dwordx4 v[34:37], v[42:43], off offset:3072 nt
	v_add_co_u32_e32 v42, vcc, s45, v42
	s_ashr_i32 s43, s42, 31
	s_nop 0
	v_addc_co_u32_e32 v43, vcc, 0, v43, vcc
	global_load_dwordx4 v[46:49], v[42:43], off nt
	s_nop 0
	global_load_dwordx4 v[42:45], v[42:43], off offset:1024 nt
	s_lshl_b64 s[4:5], s[42:43], 11
	s_ashr_i32 s37, s36, 31
	s_add_i32 s24, s24, 4
	s_waitcnt vmcnt(11)
	v_lshlrev_b32_e32 v104, 16, v73
	v_and_b32_e32 v105, 0xffff0000, v73
	s_waitcnt vmcnt(10)
	v_lshlrev_b32_e32 v102, 16, v81
	v_and_b32_e32 v103, 0xffff0000, v81
	s_waitcnt vmcnt(9)
	v_lshlrev_b32_e32 v110, 16, v77
	v_and_b32_e32 v111, 0xffff0000, v77
	v_pk_mul_f32 v[102:103], v[102:103], v[110:111]
	v_pk_mul_f32 v[110:111], v[12:13], v[96:97]
	v_and_b32_e32 v73, 0xffff0000, v80
	v_pk_fma_f32 v[100:101], v[4:5], v[100:101], v[110:111]
	v_lshlrev_b32_e32 v110, 16, v72
	v_and_b32_e32 v111, 0xffff0000, v72
	v_lshlrev_b32_e32 v72, 16, v80
	v_lshlrev_b32_e32 v80, 16, v76
	v_and_b32_e32 v81, 0xffff0000, v76
	v_pk_mul_f32 v[76:77], v[10:11], v[92:93]
	v_pk_mul_f32 v[72:73], v[72:73], v[80:81]
	v_pk_fma_f32 v[76:77], v[2:3], v[98:99], v[76:77]
	v_lshlrev_b32_e32 v114, 16, v75
	v_pk_fma_f32 v[76:77], v[22:23], v[72:73], v[76:77]
	v_and_b32_e32 v115, 0xffff0000, v75
	v_pk_mul_f32 v[80:81], v[76:77], v[110:111]
	v_lshlrev_b32_e32 v76, 16, v79
	v_and_b32_e32 v77, 0xffff0000, v79
	v_pk_mul_f32 v[76:77], v[76:77], v[114:115]
	v_pk_mul_f32 v[114:115], v[16:17], v[90:91]
	v_lshlrev_b32_e32 v98, 16, v71
	v_pk_fma_f32 v[94:95], v[8:9], v[94:95], v[114:115] op_sel:[0,1,0] op_sel_hi:[1,0,1]
	v_and_b32_e32 v99, 0xffff0000, v71
	v_pk_fma_f32 v[94:95], v[20:21], v[76:77], v[94:95]
	v_and_b32_e32 v71, 0xffff0000, v78
	v_pk_mul_f32 v[94:95], v[94:95], v[98:99]
	v_lshlrev_b32_e32 v98, 16, v70
	v_and_b32_e32 v99, 0xffff0000, v70
	v_lshlrev_b32_e32 v70, 16, v78
	v_lshlrev_b32_e32 v78, 16, v74
	v_and_b32_e32 v79, 0xffff0000, v74
	v_pk_mul_f32 v[74:75], v[14:15], v[88:89]
	v_pk_mul_f32 v[70:71], v[70:71], v[78:79]
	v_pk_fma_f32 v[74:75], v[6:7], v[86:87], v[74:75] op_sel:[0,1,0] op_sel_hi:[1,0,1]
	s_waitcnt vmcnt(6)
	v_lshlrev_b32_e32 v118, 16, v65
	v_pk_fma_f32 v[74:75], v[18:19], v[70:71], v[74:75]
	v_and_b32_e32 v119, 0xffff0000, v65
	v_pk_mul_f32 v[78:79], v[74:75], v[98:99]
	v_lshlrev_b32_e32 v74, 16, v69
	v_and_b32_e32 v75, 0xffff0000, v69
	v_pk_mul_f32 v[74:75], v[74:75], v[118:119]
	v_pk_mul_f32 v[118:119], v[12:13], v[102:103]
	v_lshlrev_b32_e32 v86, 16, v61
	v_and_b32_e32 v87, 0xffff0000, v61
	v_pk_fma_f32 v[96:97], v[4:5], v[96:97], v[118:119]
	v_lshlrev_b32_e32 v118, 16, v60
	v_and_b32_e32 v119, 0xffff0000, v60
	v_lshlrev_b32_e32 v60, 16, v68
	v_and_b32_e32 v61, 0xffff0000, v68
	v_lshlrev_b32_e32 v68, 16, v64
	v_and_b32_e32 v69, 0xffff0000, v64
	v_pk_mul_f32 v[64:65], v[10:11], v[72:73]
	v_pk_mul_f32 v[60:61], v[60:61], v[68:69]
	v_pk_fma_f32 v[64:65], v[2:3], v[92:93], v[64:65]
	v_lshlrev_b32_e32 v120, 16, v63
	v_pk_fma_f32 v[64:65], v[22:23], v[60:61], v[64:65]
	v_and_b32_e32 v121, 0xffff0000, v63
	v_pk_mul_f32 v[68:69], v[64:65], v[118:119]
	v_lshlrev_b32_e32 v64, 16, v67
	v_and_b32_e32 v65, 0xffff0000, v67
	v_pk_mul_f32 v[64:65], v[64:65], v[120:121]
	v_pk_mul_f32 v[120:121], v[16:17], v[76:77]
	v_lshlrev_b32_e32 v118, 16, v59
	v_and_b32_e32 v119, 0xffff0000, v59
	v_pk_fma_f32 v[90:91], v[8:9], v[90:91], v[120:121]
	v_lshlrev_b32_e32 v120, 16, v58
	v_and_b32_e32 v121, 0xffff0000, v58
	v_lshlrev_b32_e32 v58, 16, v66
	v_and_b32_e32 v59, 0xffff0000, v66
	v_lshlrev_b32_e32 v66, 16, v62
	v_and_b32_e32 v67, 0xffff0000, v62
	v_pk_mul_f32 v[62:63], v[14:15], v[70:71]
	v_pk_mul_f32 v[58:59], v[58:59], v[66:67]
	v_pk_fma_f32 v[62:63], v[6:7], v[88:89], v[62:63]
	v_pk_fma_f32 v[90:91], v[20:21], v[64:65], v[90:91]
	v_pk_fma_f32 v[62:63], v[18:19], v[58:59], v[62:63]
	v_pk_mul_f32 v[116:117], v[78:79], v[78:79]
	v_pk_mul_f32 v[62:63], v[62:63], v[120:121]
	v_pk_mul_f32 v[90:91], v[90:91], v[118:119]
	v_pk_mul_f32 v[66:67], v[62:63], v[62:63]
	v_pk_mul_f32 v[114:115], v[94:95], v[94:95]
	v_pk_mul_f32 v[118:119], v[90:91], v[90:91]
	v_mov_b32_e32 v88, v66
	v_mov_b32_e32 v89, v116
	v_mov_b32_e32 v116, v67
	v_pk_add_f32 v[66:67], v[88:89], v[116:117]
	v_mov_b32_e32 v88, v118
	v_mov_b32_e32 v89, v114
	v_pk_fma_f32 v[100:101], v[24:25], v[102:103], v[100:101]
	v_pk_mul_f32 v[110:111], v[80:81], v[80:81]
	v_pk_fma_f32 v[96:97], v[24:25], v[74:75], v[96:97]
	v_pk_mul_f32 v[92:93], v[68:69], v[68:69]
	v_pk_add_f32 v[66:67], v[88:89], v[66:67]
	v_mov_b32_e32 v114, v119
	v_pk_mul_f32 v[100:101], v[100:101], v[104:105]
	v_pk_mul_f32 v[86:87], v[96:97], v[86:87]
	v_pk_add_f32 v[66:67], v[114:115], v[66:67]
	v_mov_b32_e32 v88, v92
	v_mov_b32_e32 v89, v110
	v_pk_mul_f32 v[104:105], v[100:101], v[100:101]
	v_pk_mul_f32 v[96:97], v[86:87], v[86:87]
	v_pk_add_f32 v[66:67], v[88:89], v[66:67]
	v_mov_b32_e32 v110, v93
	v_pk_add_f32 v[66:67], v[110:111], v[66:67]
	v_mov_b32_e32 v88, v96
	v_mov_b32_e32 v89, v104
	v_pk_add_f32 v[66:67], v[88:89], v[66:67]
	v_mov_b32_e32 v104, v97
	v_pk_add_f32 v[66:67], v[104:105], v[66:67]
	ds_bpermute_b32 v89, v106, v67
	ds_bpermute_b32 v88, v106, v66
	v_mov_b64_e32 v[104:105], s[44:45]
	v_lshl_add_u64 v[98:99], s[30:31], 0, v[0:1]
	s_waitcnt lgkmcnt(0)
	v_pk_add_f32 v[66:67], v[66:67], v[88:89]
	ds_bpermute_b32 v89, v107, v67
	ds_bpermute_b32 v88, v107, v66
	s_waitcnt lgkmcnt(0)
	v_pk_add_f32 v[66:67], v[66:67], v[88:89]
	ds_bpermute_b32 v89, v108, v67
	ds_bpermute_b32 v88, v108, v66
	s_waitcnt lgkmcnt(0)
	v_pk_add_f32 v[66:67], v[66:67], v[88:89]
	s_nop 0
	v_pk_fma_f32 v[66:67], v[66:67], s[46:47], v[104:105] op_sel_hi:[1,0,0]
	s_nop 0
	v_mul_f32_e32 v88, 0x4b800000, v67
	v_cmp_gt_f32_e64 s[40:41], s10, v67
	v_cmp_gt_f32_e32 vcc, s10, v66
	s_nop 0
	v_cndmask_b32_e64 v67, v67, v88, s[40:41]
	v_rsq_f32_e32 v67, v67
	s_nop 0
	v_mul_f32_e32 v88, 0x45800000, v67
	v_cndmask_b32_e64 v88, v67, v88, s[40:41]
	v_mul_f32_e32 v67, 0x4b800000, v66
	v_cndmask_b32_e32 v66, v66, v67, vcc
	v_rsq_f32_e32 v66, v66
	v_pk_mul_f32 v[78:79], v[78:79], v[88:89] op_sel_hi:[1,0]
	v_pk_mul_f32 v[92:93], v[94:95], v[88:89] op_sel_hi:[1,0]
	v_pk_mul_f32 v[80:81], v[80:81], v[88:89] op_sel_hi:[1,0]
	v_pk_mul_f32 v[88:89], v[100:101], v[88:89] op_sel_hi:[1,0]
	v_pk_mul_f32 v[78:79], v[30:31], v[78:79]
	v_pk_mul_f32 v[92:93], v[32:33], v[92:93]
	v_pk_mul_f32 v[80:81], v[26:27], v[80:81]
	v_pk_mul_f32 v[88:89], v[28:29], v[88:89]
	v_cvt_pk_bf16_f32 v78, v78, v79
	v_cvt_pk_bf16_f32 v79, v92, v93
	v_cvt_pk_bf16_f32 v80, v80, v81
	v_cvt_pk_bf16_f32 v81, v88, v89
	v_mul_f32_e32 v67, 0x45800000, v66
	global_store_dwordx4 v[98:99], v[78:81], off
	s_nop 1
	v_cndmask_b32_e32 v78, v66, v67, vcc
	v_pk_mul_f32 v[62:63], v[62:63], v[78:79] op_sel_hi:[1,0]
	s_nop 0
	v_pk_mul_f32 v[62:63], v[30:31], v[62:63]
	s_nop 0
	v_cvt_pk_bf16_f32 v66, v62, v63
	v_pk_mul_f32 v[62:63], v[90:91], v[78:79] op_sel_hi:[1,0]
	s_nop 0
	v_pk_mul_f32 v[62:63], v[32:33], v[62:63]
	s_nop 0
	v_cvt_pk_bf16_f32 v67, v62, v63
	v_pk_mul_f32 v[62:63], v[68:69], v[78:79] op_sel_hi:[1,0]
	s_nop 0
	v_pk_mul_f32 v[62:63], v[26:27], v[62:63]
	s_nop 0
	v_cvt_pk_bf16_f32 v68, v62, v63
	v_pk_mul_f32 v[62:63], v[86:87], v[78:79] op_sel_hi:[1,0]
	s_nop 0
	v_pk_mul_f32 v[62:63], v[28:29], v[62:63]
	s_nop 0
	v_cvt_pk_bf16_f32 v69, v62, v63
	v_lshl_add_u64 v[62:63], s[26:27], 0, v[0:1]
	global_store_dwordx4 v[62:63], v[66:69], off
	s_waitcnt vmcnt(6)
	v_and_b32_e32 v62, 0xffff0000, v54
	v_lshlrev_b32_e32 v63, 16, v54
	s_waitcnt vmcnt(5)
	v_and_b32_e32 v66, 0xffff0000, v50
	v_lshlrev_b32_e32 v67, 16, v50
	v_and_b32_e32 v54, 0xffff0000, v55
	v_lshlrev_b32_e32 v55, 16, v55
	v_and_b32_e32 v50, 0xffff0000, v51
	v_lshlrev_b32_e32 v51, 16, v51
	v_pk_mul_f32 v[94:95], v[54:55], v[50:51]
	v_lshlrev_b32_e32 v50, 16, v56
	v_and_b32_e32 v51, 0xffff0000, v56
	v_lshlrev_b32_e32 v54, 16, v52
	v_and_b32_e32 v55, 0xffff0000, v52
	v_pk_mul_f32 v[98:99], v[50:51], v[54:55]
	v_lshlrev_b32_e32 v50, 16, v57
	v_and_b32_e32 v51, 0xffff0000, v57
	v_lshlrev_b32_e32 v52, 16, v53
	v_and_b32_e32 v53, 0xffff0000, v53
	v_pk_mul_f32 v[86:87], v[62:63], v[66:67]
	v_pk_mul_f32 v[100:101], v[50:51], v[52:53]
	v_lshlrev_b32_e32 v50, 16, v41
	v_and_b32_e32 v51, 0xffff0000, v41
	v_lshlrev_b32_e32 v54, 16, v40
	v_and_b32_e32 v55, 0xffff0000, v40
	v_pk_mul_f32 v[40:41], v[10:11], v[60:61]
	v_lshlrev_b32_e32 v56, 16, v39
	v_and_b32_e32 v57, 0xffff0000, v39
	v_lshlrev_b32_e32 v66, 16, v38
	v_and_b32_e32 v67, 0xffff0000, v38
	v_pk_mul_f32 v[38:39], v[14:15], v[58:59]
	v_pk_fma_f32 v[40:41], v[2:3], v[72:73], v[40:41]
	v_pk_fma_f32 v[38:39], v[6:7], v[70:71], v[38:39]
	s_waitcnt vmcnt(3)
	v_lshlrev_b32_e32 v70, 16, v46
	v_and_b32_e32 v71, 0xffff0000, v46
	s_waitcnt vmcnt(2)
	v_lshlrev_b32_e32 v72, 16, v42
	v_and_b32_e32 v73, 0xffff0000, v42
	v_lshlrev_b32_e32 v46, 16, v47
	v_and_b32_e32 v47, 0xffff0000, v47
	v_lshlrev_b32_e32 v42, 16, v43
	v_and_b32_e32 v43, 0xffff0000, v43
	v_pk_mul_f32 v[90:91], v[46:47], v[42:43]
	v_lshlrev_b32_e32 v42, 16, v48
	v_and_b32_e32 v43, 0xffff0000, v48
	v_lshlrev_b32_e32 v46, 16, v44
	v_and_b32_e32 v47, 0xffff0000, v44
	v_pk_mul_f32 v[92:93], v[42:43], v[46:47]
	v_lshlrev_b32_e32 v42, 16, v49
	v_and_b32_e32 v43, 0xffff0000, v49
	v_lshlrev_b32_e32 v44, 16, v45
	v_and_b32_e32 v45, 0xffff0000, v45
	v_pk_mul_f32 v[96:97], v[42:43], v[44:45]
	v_lshlrev_b32_e32 v42, 16, v37
	v_and_b32_e32 v43, 0xffff0000, v37
	v_lshlrev_b32_e32 v46, 16, v36
	v_and_b32_e32 v47, 0xffff0000, v36
	v_pk_mul_f32 v[36:37], v[10:11], v[98:99]
	v_pk_mul_f32 v[62:63], v[16:17], v[64:65]
	v_pk_fma_f32 v[36:37], v[2:3], v[60:61], v[36:37]
	v_pk_mul_f32 v[60:61], v[16:17], v[94:95] op_sel:[0,1] op_sel_hi:[1,0]
	v_lshlrev_b32_e32 v48, 16, v35
	v_and_b32_e32 v49, 0xffff0000, v35
	v_pk_fma_f32 v[60:61], v[8:9], v[64:65], v[60:61]
	v_lshlrev_b32_e32 v64, 16, v34
	v_and_b32_e32 v65, 0xffff0000, v34
	v_pk_mul_f32 v[34:35], v[14:15], v[86:87] op_sel:[0,1] op_sel_hi:[1,0]
	v_pk_mul_f32 v[88:89], v[70:71], v[72:73]
	v_pk_fma_f32 v[34:35], v[6:7], v[58:59], v[34:35]
	v_pk_fma_f32 v[62:63], v[8:9], v[76:77], v[62:63]
	v_pk_fma_f32 v[38:39], v[18:19], v[86:87], v[38:39] op_sel:[0,1,0] op_sel_hi:[1,0,1]
	v_pk_fma_f32 v[34:35], v[18:19], v[88:89], v[34:35]
	v_pk_fma_f32 v[62:63], v[20:21], v[94:95], v[62:63] op_sel:[0,1,0] op_sel_hi:[1,0,1]
	v_pk_mul_f32 v[38:39], v[38:39], v[66:67]
	v_pk_fma_f32 v[60:61], v[20:21], v[90:91], v[60:61]
	v_pk_mul_f32 v[58:59], v[34:35], v[64:65]
	v_pk_mul_f32 v[56:57], v[62:63], v[56:57]
	v_pk_mul_f32 v[66:67], v[38:39], v[38:39]
	v_pk_mul_f32 v[48:49], v[60:61], v[48:49]
	v_pk_mul_f32 v[34:35], v[58:59], v[58:59]
	v_pk_mul_f32 v[52:53], v[12:13], v[74:75]
	v_pk_fma_f32 v[40:41], v[22:23], v[98:99], v[40:41]
	v_pk_mul_f32 v[62:63], v[56:57], v[56:57]
	v_pk_mul_f32 v[44:45], v[12:13], v[100:101]
	v_pk_fma_f32 v[36:37], v[22:23], v[92:93], v[36:37]
	v_pk_mul_f32 v[60:61], v[48:49], v[48:49]
	v_mov_b32_e32 v64, v34
	v_mov_b32_e32 v65, v66
	v_mov_b32_e32 v66, v35
	v_pk_fma_f32 v[52:53], v[4:5], v[102:103], v[52:53]
	v_pk_mul_f32 v[40:41], v[40:41], v[54:55]
	v_pk_fma_f32 v[44:45], v[4:5], v[74:75], v[44:45]
	v_pk_mul_f32 v[46:47], v[36:37], v[46:47]
	v_pk_add_f32 v[34:35], v[64:65], v[66:67]
	v_mov_b32_e32 v64, v60
	v_mov_b32_e32 v65, v62
	v_pk_fma_f32 v[52:53], v[24:25], v[100:101], v[52:53]
	v_pk_mul_f32 v[54:55], v[40:41], v[40:41]
	v_pk_fma_f32 v[44:45], v[24:25], v[96:97], v[44:45]
	v_pk_mul_f32 v[36:37], v[46:47], v[46:47]
	v_pk_add_f32 v[34:35], v[64:65], v[34:35]
	v_mov_b32_e32 v62, v61
	v_pk_mul_f32 v[50:51], v[52:53], v[50:51]
	v_pk_mul_f32 v[42:43], v[44:45], v[42:43]
	v_pk_add_f32 v[34:35], v[62:63], v[34:35]
	v_mov_b32_e32 v60, v36
	v_mov_b32_e32 v61, v54
	v_pk_mul_f32 v[52:53], v[50:51], v[50:51]
	v_pk_mul_f32 v[44:45], v[42:43], v[42:43]
	v_pk_add_f32 v[34:35], v[60:61], v[34:35]
	v_mov_b32_e32 v54, v37
	v_pk_add_f32 v[34:35], v[54:55], v[34:35]
	v_mov_b32_e32 v36, v44
	v_mov_b32_e32 v37, v52
	v_pk_add_f32 v[34:35], v[36:37], v[34:35]
	v_mov_b32_e32 v52, v45
	v_pk_add_f32 v[34:35], v[52:53], v[34:35]
	ds_bpermute_b32 v37, v106, v35
	ds_bpermute_b32 v36, v106, v34
	v_lshl_add_u64 v[68:69], v[84:85], 0, s[4:5]
	s_lshl_b64 s[4:5], s[36:37], 11
	s_add_u32 s26, s26, 0x2000
	s_addc_u32 s27, s27, 0
	s_waitcnt lgkmcnt(0)
	v_pk_add_f32 v[34:35], v[34:35], v[36:37]
	ds_bpermute_b32 v37, v107, v35
	ds_bpermute_b32 v36, v107, v34
	s_add_u32 s28, s28, 0x6000
	s_addc_u32 s29, s29, 0
	s_add_u32 s30, s30, 0x2000
	s_addc_u32 s31, s31, 0
	s_waitcnt lgkmcnt(0)
	v_pk_add_f32 v[34:35], v[34:35], v[36:37]
	ds_bpermute_b32 v37, v108, v35
	ds_bpermute_b32 v36, v108, v34
	s_add_u32 s34, s34, 0x6000
	s_addc_u32 s35, s35, 0
	s_cmp_ge_i32 s24, s39
	s_waitcnt lgkmcnt(0)
	v_pk_add_f32 v[34:35], v[34:35], v[36:37]
	s_nop 0
	v_pk_fma_f32 v[44:45], v[34:35], s[46:47], v[104:105] op_sel_hi:[1,0,0]
	s_nop 0
	v_mul_f32_e32 v34, 0x4b800000, v45
	v_cmp_gt_f32_e64 s[40:41], s10, v45
	v_cmp_gt_f32_e32 vcc, s10, v44
	s_nop 0
	v_cndmask_b32_e64 v34, v45, v34, s[40:41]
	v_rsq_f32_e32 v34, v34
	s_nop 0
	v_mul_f32_e32 v35, 0x45800000, v34
	v_cndmask_b32_e64 v52, v34, v35, s[40:41]
	v_pk_mul_f32 v[34:35], v[38:39], v[52:53] op_sel_hi:[1,0]
	v_pk_mul_f32 v[36:37], v[56:57], v[52:53] op_sel_hi:[1,0]
	v_pk_mul_f32 v[34:35], v[30:31], v[34:35]
	v_pk_mul_f32 v[36:37], v[32:33], v[36:37]
	v_cvt_pk_bf16_f32 v34, v34, v35
	v_cvt_pk_bf16_f32 v35, v36, v37
	v_pk_mul_f32 v[36:37], v[40:41], v[52:53] op_sel_hi:[1,0]
	v_pk_mul_f32 v[38:39], v[50:51], v[52:53] op_sel_hi:[1,0]
	v_pk_mul_f32 v[36:37], v[26:27], v[36:37]
	v_pk_mul_f32 v[38:39], v[28:29], v[38:39]
	v_cvt_pk_bf16_f32 v36, v36, v37
	v_cvt_pk_bf16_f32 v37, v38, v39
	global_store_dwordx4 v[68:69], v[34:37], off offset:1024
	s_nop 1
	v_mul_f32_e32 v34, 0x4b800000, v44
	v_cndmask_b32_e32 v34, v44, v34, vcc
	v_rsq_f32_e32 v34, v34
	s_nop 0
	v_mul_f32_e32 v35, 0x45800000, v34
	v_cndmask_b32_e32 v38, v34, v35, vcc
	v_pk_mul_f32 v[34:35], v[58:59], v[38:39] op_sel_hi:[1,0]
	v_pk_mul_f32 v[36:37], v[48:49], v[38:39] op_sel_hi:[1,0]
	v_pk_mul_f32 v[34:35], v[30:31], v[34:35]
	v_pk_mul_f32 v[36:37], v[32:33], v[36:37]
	v_cvt_pk_bf16_f32 v34, v34, v35
	v_cvt_pk_bf16_f32 v35, v36, v37
	v_pk_mul_f32 v[36:37], v[46:47], v[38:39] op_sel_hi:[1,0]
	v_pk_mul_f32 v[38:39], v[42:43], v[38:39] op_sel_hi:[1,0]
	v_pk_mul_f32 v[36:37], v[26:27], v[36:37]
	v_pk_mul_f32 v[38:39], v[28:29], v[38:39]
	v_cvt_pk_bf16_f32 v36, v36, v37
	v_cvt_pk_bf16_f32 v37, v38, v39
	v_lshl_add_u64 v[38:39], v[84:85], 0, s[4:5]
	global_store_dwordx4 v[38:39], v[34:37], off offset:1024
	s_cbranch_scc0 .LBB0_113
